# attn dense loops: drop in-loop vmcnt waits, stage K/V to LDS late in exp phase, cross-half max only on rescale path
# baseline (speedup 1.0000x reference)
; DI int tid_() { int t = threadIdx.x; asm volatile("" : "+v"(t)); return t; }
; template <int DQK, bool BAND, int QT> ...
;     ...
;   const int tid = tid_(), lane = tid & 63, w = tid >> 6, h = lane >> 5, ql = lane & 31;
;   float* bias_l = (float*)(lds + 2 * ST);
;   if (BAND) { if (tid < 129) bias_l[tid] = bias_g[tid]; }
;   bf16x8 qf[QT][NKS];
; #pragma unroll
;   for (int qt = 0; qt < QT; ++qt)
; #pragma unroll
;     for (int ks = 0; ks < NKS; ++ks) qf[qt][ks] = *(const bf16x8*)(Q + (size_t)(w * WQ + qt * 32 + ql) * DQK + ks * 16 + h * 8);
;   f32x16 o[2][QT];
; #pragma unroll
;   for (int a = 0; a < 2; ++a)
; #pragma unroll
;     for (int b = 0; b < QT; ++b)
; #pragma unroll
;       for (int r = 0; r < 16; ++r) o[a][b][r] = 0.f;
;   float m[QT], l[QT];
; #pragma unroll
;   for (int qt = 0; qt < QT; ++qt) { m[qt] = -1e30f; l[qt] = 0.f; }
;   u32x4 rk[NKL], rv[2];
;   const int vrow0 = tid >> 3, vch = tid & 7;
;   unsigned klds[NKL];
; #pragma unroll
;   for (int i = 0; i < NKL; ++i) { const int idx = tid + i * 256, kr = idx / KV4, kc = idx - kr * KV4; klds[i] = kr * KROW + kc * 16; }
;   const unsigned koff0 = (unsigned)tid * 16u;
;   const unsigned voff0 = (unsigned)(vrow0 * ldv + vch * 8) * 2u, vstep = (unsigned)(32 * ldv) * 2u;
;   const unsigned vlds0 = KST + vrow0 * LROW + vch * 16;
;   auto gload = [&](int kt) {
;     const char* kb = (const char*)Kp + (size_t)kt * (DQK * 2);
;     const char* vb = (const char*)Vt + (size_t)kt * 2;
; #pragma unroll
;     for (int i = 0; i < NKL; ++i) rk[i] = *(const u32x4*)(kb + (koff0 + i * 4096u));
; #pragma unroll
;     for (int i = 0; i < 2; ++i) rv[i] = *(const u32x4*)(vb + (voff0 + i * vstep));
;   };
;   auto lstore = [&](char* st) {
; #pragma unroll
;     for (int i = 0; i < NKL; ++i) *(u32x4*)(st + klds[i]) = rk[i];
; #pragma unroll
;     for (int i = 0; i < 2; ++i) *(u32x4*)(st + vlds0 + i * 32 * LROW) = rv[i];
;   };
;   gload(kbeg);
;   lstore(lds);
;   __syncthreads();
;   const int pr = (ql & ~12) | ((ql & 4) << 1) | ((ql & 8) >> 1);
;   const int k_rd = pr * KROW + h * 16;
;   const int v_rd = KST + ql * LROW + h * 16;
.LBB0_826:
	s_and_b64 vcc, exec, s[0:1]
	s_cbranch_vccz .LBB0_838
	v_readlane_b32 s0, v249, 58
	s_sub_i32 s0, s26, s0
	s_ashr_i32 s1, s0, 3
	s_ashr_i32 s7, s0, 31
	s_abs_i32 s0, s1
	v_readlane_b32 s2, v248, 3
	s_mul_hi_u32 s2, s0, s2
	v_readlane_b32 s5, v248, 2
	s_mul_i32 s3, s2, s5
	s_sub_i32 s0, s0, s3
	s_add_i32 s3, s2, 1
	s_sub_i32 s4, s0, s5
	s_cmp_ge_u32 s0, s5
	s_cselect_b32 s2, s3, s2
	s_cselect_b32 s0, s4, s0
	s_add_i32 s3, s2, 1
	s_cmp_ge_u32 s0, s5
	s_cselect_b32 s0, s3, s2
	s_xor_b32 s40, s0, s7
	s_sub_i32 s0, s40, s7
	s_lshl_b32 s2, s0, s60
	s_sub_i32 s1, s1, s2
	s_lshl_b32 s2, s0, 3
	v_readlane_b32 s3, v249, 31
	s_or_b32 s2, s2, s3
	s_lshl_b32 s4, s0, 1
	v_readlane_b32 s41, v250, 44
	s_ashr_i32 s3, s2, 31
	s_or_b32 s26, s4, s41
	s_lshl_b32 s4, s1, 8
	s_lshl_b64 s[2:3], s[2:3], s20
	s_ashr_i32 s27, s26, 31
	s_ashr_i32 s5, s4, 31
	s_add_u32 s2, s2, s4
	s_addc_u32 s3, s3, s5
	s_lshl_b64 s[2:3], s[2:3], 7
	v_readlane_b32 s1, v250, 53
	s_add_u32 s34, s1, s2
	v_readlane_b32 s1, v250, 54
	s_addc_u32 s35, s1, s3
	v_readlane_b32 s1, v248, 1
	s_lshl_b64 s[2:3], s[26:27], s1
	v_readlane_b32 s1, v250, 55
	s_add_u32 s38, s1, s2
	v_readlane_b32 s1, v250, 56
	v_mov_b32_e32 v5, v199
	s_addc_u32 s39, s1, s3
	v_readlane_b32 s1, v249, 61
	v_readlane_b32 s6, v249, 63
	v_lshlrev_b32_e32 v2, 4, v5
	v_ashrrev_i32_e32 v18, 3, v5
	s_mul_hi_i32 s27, s26, s1
	s_mul_i32 s26, s26, s1
	v_and_b32_e32 v4, 0x70, v2
	v_mul_lo_u32 v0, v18, s6
	v_bfe_u32 v196, v5, 5, 1
	v_and_b32_e32 v180, 0xffffffdf, v5
	s_lshl_b64 s[26:27], s[26:27], 1
	v_readlane_b32 s42, v250, 28
	v_or_b32_e32 v6, v4, v0
	s_waitcnt vmcnt(16)
	v_or_b32_e32 v178, 32, v5
	v_lshlrev_b32_e32 v0, 4, v196
	v_ashrrev_i32_e32 v181, 31, v180
	v_readlane_b32 s43, v250, 29
	s_add_u32 s26, s42, s26
	v_ashrrev_i32_e32 v179, 31, v178
	v_lshlrev_b64 v[12:13], 7, v[180:181]
	v_lshl_add_u64 v[16:17], s[34:35], 0, v[0:1]
	s_addc_u32 s27, s43, s27
	v_lshlrev_b64 v[14:15], 7, v[178:179]
	v_lshl_add_u64 v[12:13], v[16:17], 0, v[12:13]
	v_add_u32_e32 v8, 0x1000, v2
	global_load_dwordx4 v[130:133], v2, s[38:39]
	global_load_dwordx4 v[134:137], v8, s[38:39]
	v_add_u32_e32 v10, s1, v6
	global_load_dwordx4 v[138:141], v6, s[26:27]
	global_load_dwordx4 v[142:145], v10, s[26:27]
	v_lshl_add_u64 v[14:15], v[16:17], 0, v[14:15]
	global_load_dwordx4 v[146:149], v[12:13], off
	global_load_dwordx4 v[150:153], v[12:13], off offset:32
	global_load_dwordx4 v[154:157], v[12:13], off offset:64
	global_load_dwordx4 v[158:161], v[12:13], off offset:96
	global_load_dwordx4 v[162:165], v[14:15], off
	global_load_dwordx4 v[166:169], v[14:15], off offset:32
	global_load_dwordx4 v[170:173], v[14:15], off offset:64
	global_load_dwordx4 v[174:177], v[14:15], off offset:96
	v_ashrrev_i32_e32 v19, 31, v5
	v_add_u32_e32 v20, 0x100, v5
	v_lshrrev_b32_e32 v13, 29, v19
	v_ashrrev_i32_e32 v14, 31, v20
	v_add_u32_e32 v13, v5, v13
	v_lshrrev_b32_e32 v14, 29, v14
	v_mad_u64_u32 v[182:183], s[26:27], v18, s16, v[4:5]
	v_ashrrev_i32_e32 v13, 3, v13
	v_add_u32_e32 v4, v20, v14
	v_lshlrev_b32_e32 v16, 7, v13
	v_ashrrev_i32_e32 v17, 3, v4
	v_lshlrev_b32_e32 v15, 4, v20
	v_sub_u32_e32 v4, v2, v16
	v_lshlrev_b32_e32 v16, 7, v17
	v_mad_u64_u32 v[184:185], s[26:27], v13, s16, v[4:5]
	v_sub_u32_e32 v4, v15, v16
	v_mad_u64_u32 v[186:187], s[26:27], v17, s16, v[4:5]
	s_lshl_b32 s26, s40, 1
	s_or_b32 s26, s41, s26
	s_lshl_b32 s7, s7, 1
	s_sub_i32 s7, s26, s7
	v_readlane_b32 s26, v248, 4
	v_and_b32_e32 v12, 31, v5
	v_add_u32_e32 v4, 0, v184
	s_mul_hi_i32 s27, s26, s7
	s_mul_i32 s7, s26, s7
	v_add_u32_e32 v14, 0, v182
	v_add_u32_e32 v13, 0, v186
	v_mul_u32_u24_e32 v183, 0x90, v12
	v_lshlrev_b32_e32 v12, 1, v5
	s_add_u32 s26, s7, 0x179d5980
	s_waitcnt vmcnt(11)
	ds_write_b128 v4, v[130:133]
	s_waitcnt vmcnt(10)
	ds_write_b128 v13, v[134:137]
	s_waitcnt vmcnt(9)
	ds_write_b128 v14, v[138:141] offset:9216
	s_waitcnt vmcnt(8)
	ds_write_b128 v14, v[142:145] offset:13824
	v_and_b32_e32 v4, 19, v5
	v_lshrrev_b32_e32 v5, 1, v5
	v_and_b32_e32 v12, 8, v12
	v_and_b32_e32 v5, 4, v5
	s_addc_u32 s27, s27, 0
	v_or3_b32 v4, v4, v12, v5
	v_cmp_lt_i32_e32 vcc, v221, v220
	s_add_u32 s2, s2, 0x175d7900
	v_mov_b32_e32 v3, v1
	v_mov_b32_e32 v9, v1
	v_mov_b32_e32 v7, v1
	v_mov_b32_e32 v11, v1
	v_mul_u32_u24_e32 v185, 0x90, v4
	v_cndmask_b32_e32 v4, v219, v221, vcc
	s_addc_u32 s3, s3, 0
	v_mov_b32_e32 v50, v1
	v_mov_b32_e32 v51, v1
	v_lshlrev_b32_e32 v179, 2, v4
	v_lshl_add_u64 v[188:189], s[26:27], 0, v[6:7]
	v_lshl_add_u64 v[190:191], s[26:27], 0, v[10:11]
	v_lshl_add_u64 v[192:193], s[2:3], 0, v[2:3]
	v_lshl_add_u64 v[194:195], s[2:3], 0, v[8:9]
	v_mov_b32_e32 v52, v1
	v_mov_b32_e32 v53, v1
	v_mov_b32_e32 v54, v1
	v_mov_b32_e32 v55, v1
	v_mov_b32_e32 v56, v1
	v_mov_b32_e32 v57, v1
	v_mov_b32_e32 v58, v1
	v_mov_b32_e32 v59, v1
	v_mov_b32_e32 v60, v1
	v_mov_b32_e32 v61, v1
	v_mov_b32_e32 v62, v1
	v_mov_b32_e32 v63, v1
	v_mov_b32_e32 v64, v1
	v_mov_b32_e32 v65, v1
	v_mov_b64_e32 v[18:19], v[50:51]
	v_mov_b64_e32 v[34:35], v[50:51]
	v_mov_b64_e32 v[2:3], v[50:51]
	s_mov_b32 s1, 0
	s_mov_b32 s6, 64
	v_mov_b32_e32 v197, 0xf149f2ca
	v_mov_b32_e32 v187, 0
	v_mov_b32_e32 v181, 0
	v_mov_b32_e32 v202, 0xf149f2ca
	v_mov_b64_e32 v[20:21], v[52:53]
	v_mov_b64_e32 v[22:23], v[54:55]
	v_mov_b64_e32 v[24:25], v[56:57]
	v_mov_b64_e32 v[26:27], v[58:59]
	v_mov_b64_e32 v[28:29], v[60:61]
	v_mov_b64_e32 v[30:31], v[62:63]
	v_mov_b64_e32 v[32:33], v[64:65]
	v_mov_b64_e32 v[36:37], v[52:53]
	v_mov_b64_e32 v[38:39], v[54:55]
	v_mov_b64_e32 v[40:41], v[56:57]
	v_mov_b64_e32 v[42:43], v[58:59]
	v_mov_b64_e32 v[44:45], v[60:61]
	v_mov_b64_e32 v[46:47], v[62:63]
	v_mov_b64_e32 v[48:49], v[64:65]
	v_mov_b64_e32 v[4:5], v[52:53]
	v_mov_b64_e32 v[6:7], v[54:55]
	v_mov_b64_e32 v[8:9], v[56:57]
	v_mov_b64_e32 v[10:11], v[58:59]
	v_mov_b64_e32 v[12:13], v[60:61]
	v_mov_b64_e32 v[14:15], v[62:63]
	v_mov_b64_e32 v[16:17], v[64:65]
	s_waitcnt vmcnt(0) lgkmcnt(0)
	s_barrier
	s_branch .LBB0_829
; DI unsigned pk2(float a, float b) { f32x2 v = {a, b}; bf16x2_t r = __builtin_convertvector(v, bf16x2_t); return __builtin_bit_cast(unsigned, r); }
; template <int DQK, bool BAND, int QT> ...
;     ...
;   auto lstore = [&](char* st) {
; #pragma unroll
;     for (int i = 0; i < NKL; ++i) *(u32x4*)(st + klds[i]) = rk[i];
; #pragma unroll
;     for (int i = 0; i < 2; ++i) *(u32x4*)(st + vlds0 + i * 32 * LROW) = rv[i];
;   };
;     ...
;         const float mc = -m[qt] * cc;
;         float ls = 0.f;
; #pragma unroll
;         for (int a = 0; a < 2; ++a) {
; #pragma unroll
;           for (int r = 0; r < 16; ++r) { const float pv = __builtin_amdgcn_exp2f(fmaf(s[a][qt][r], cc, mc)); s[a][qt][r] = pv; ls += pv; }
; #pragma unroll
;           for (int s2 = 0; s2 < 2; ++s2) {
;             u32x4 pk;
;             pk.x = pk2(s[a][qt][8 * s2 + 0], s[a][qt][8 * s2 + 1]);
;             pk.y = pk2(s[a][qt][8 * s2 + 2], s[a][qt][8 * s2 + 3]);
;             pk.z = pk2(s[a][qt][8 * s2 + 4], s[a][qt][8 * s2 + 5]);
;             pk.w = pk2(s[a][qt][8 * s2 + 6], s[a][qt][8 * s2 + 7]);
;             pf[qt][a * 2 + s2] = __builtin_bit_cast(bf16x8, pk);
;           }
;         }
;         l[qt] += ls;
.LBB0_828:
	v_mul_f32_e32 v203, 0xbe38aa3b, v202
	v_fmamk_f32 v114, v114, 0x3e38aa3b, v203
	v_exp_f32_e32 v204, v114
	v_fmamk_f32 v114, v115, 0x3e38aa3b, v203
	v_exp_f32_e32 v206, v114
	v_fmamk_f32 v114, v116, 0x3e38aa3b, v203
	v_exp_f32_e32 v207, v114
	v_fmamk_f32 v114, v117, 0x3e38aa3b, v203
	v_exp_f32_e32 v208, v114
	v_fmamk_f32 v114, v118, 0x3e38aa3b, v203
	v_exp_f32_e32 v209, v114
	v_fmamk_f32 v114, v119, 0x3e38aa3b, v203
	v_exp_f32_e32 v210, v114
	v_fmamk_f32 v114, v120, 0x3e38aa3b, v203
	v_exp_f32_e32 v211, v114
	v_fmamk_f32 v114, v121, 0x3e38aa3b, v203
	v_exp_f32_e32 v212, v114
	v_fmamk_f32 v114, v122, 0x3e38aa3b, v203
	v_cvt_pk_bf16_f32 v118, v204, v206
	v_add_f32_e32 v204, 0, v204
	v_exp_f32_e32 v122, v114
	v_fmamk_f32 v114, v123, 0x3e38aa3b, v203
	v_add_f32_e32 v204, v206, v204
	v_exp_f32_e32 v123, v114
	v_fmamk_f32 v114, v124, 0x3e38aa3b, v203
	v_add_f32_e32 v204, v207, v204
	v_exp_f32_e32 v124, v114
	v_fmamk_f32 v114, v125, 0x3e38aa3b, v203
	v_add_f32_e32 v204, v208, v204
	v_exp_f32_e32 v125, v114
	v_fmamk_f32 v114, v126, 0x3e38aa3b, v203
	v_add_f32_e32 v204, v209, v204
	v_exp_f32_e32 v126, v114
	v_fmamk_f32 v114, v127, 0x3e38aa3b, v203
	v_add_f32_e32 v204, v210, v204
	v_exp_f32_e32 v127, v114
	v_fmamk_f32 v114, v128, 0x3e38aa3b, v203
	v_add_f32_e32 v204, v211, v204
	v_exp_f32_e32 v128, v114
	v_fmamk_f32 v114, v129, 0x3e38aa3b, v203
	v_add_f32_e32 v204, v212, v204
	v_exp_f32_e32 v129, v114
	v_cvt_pk_bf16_f32 v114, v122, v123
	v_add_f32_e32 v122, v122, v204
	v_add_f32_e32 v122, v123, v122
	v_fmamk_f32 v98, v98, 0x3e38aa3b, v203
	v_add_f32_e32 v122, v124, v122
	v_exp_f32_e32 v123, v98
	v_fmamk_f32 v98, v99, 0x3e38aa3b, v203
	v_cvt_pk_bf16_f32 v115, v124, v125
	v_add_f32_e32 v122, v125, v122
	v_exp_f32_e32 v124, v98
	v_fmamk_f32 v98, v100, 0x3e38aa3b, v203
	v_add_f32_e32 v122, v126, v122
	v_exp_f32_e32 v125, v98
	v_fmamk_f32 v98, v101, 0x3e38aa3b, v203
	v_cvt_pk_bf16_f32 v116, v126, v127
	v_add_f32_e32 v122, v127, v122
	v_exp_f32_e32 v126, v98
	v_fmamk_f32 v98, v102, 0x3e38aa3b, v203
	v_add_f32_e32 v122, v128, v122
	v_exp_f32_e32 v127, v98
	v_fmamk_f32 v98, v103, 0x3e38aa3b, v203
	v_cvt_pk_bf16_f32 v117, v128, v129
	v_add_f32_e32 v122, v129, v122
	v_exp_f32_e32 v128, v98
	v_fmamk_f32 v98, v104, 0x3e38aa3b, v203
	v_exp_f32_e32 v129, v98
	v_fmamk_f32 v98, v105, 0x3e38aa3b, v203
	v_add_f32_e32 v122, v123, v122
	v_exp_f32_e32 v204, v98
	v_fmamk_f32 v98, v106, 0x3e38aa3b, v203
	v_add_f32_e32 v122, v124, v122
	v_exp_f32_e32 v106, v98
	v_fmamk_f32 v98, v107, 0x3e38aa3b, v203
	v_add_f32_e32 v122, v125, v122
	v_exp_f32_e32 v107, v98
	v_fmamk_f32 v98, v108, 0x3e38aa3b, v203
	v_add_f32_e32 v122, v126, v122
	v_exp_f32_e32 v108, v98
	v_fmamk_f32 v98, v109, 0x3e38aa3b, v203
	v_add_f32_e32 v122, v127, v122
	v_exp_f32_e32 v109, v98
	v_fmamk_f32 v98, v110, 0x3e38aa3b, v203
	v_add_f32_e32 v122, v128, v122
	v_exp_f32_e32 v110, v98
	v_fmamk_f32 v98, v111, 0x3e38aa3b, v203
	v_add_f32_e32 v122, v129, v122
	v_exp_f32_e32 v111, v98
	v_fmamk_f32 v98, v112, 0x3e38aa3b, v203
	v_add_f32_e32 v122, v204, v122
	v_exp_f32_e32 v112, v98
	v_cvt_pk_bf16_f32 v98, v106, v107
	v_add_f32_e32 v106, v106, v122
	v_add_f32_e32 v106, v107, v106
	v_fmac_f32_e32 v203, 0x3e38aa3b, v113
	v_add_f32_e32 v106, v108, v106
	v_exp_f32_e32 v113, v203
	v_add_f32_e32 v106, v109, v106
	v_add_f32_e32 v106, v110, v106
	v_add_f32_e32 v106, v111, v106
	v_add_f32_e32 v106, v112, v106
	v_add_f32_e32 v106, v113, v106
	v_add_f32_e32 v181, v181, v106
	s_andn2_b64 vcc, exec, s[2:3]
	s_cbranch_vccnz .Lgqa_nostage
	s_andn2_b32 s2, 1, s1
	s_mulk_i32 s2, 0x4800
	v_add_u32_e32 v203, s2, v184
	s_waitcnt vmcnt(3)
	ds_write_b128 v203, v[130:133]
	v_add_u32_e32 v203, s2, v186
	s_waitcnt vmcnt(2)
	ds_write_b128 v203, v[134:137]
	v_add_u32_e32 v203, s2, v182
	s_waitcnt vmcnt(1)
	ds_write_b128 v203, v[138:141] offset:9216
	s_waitcnt vmcnt(0)
	ds_write_b128 v203, v[142:145] offset:13824
; #define MFMA(a, b, c) __builtin_amdgcn_mfma_f32_32x32x16_bf16((a), (b), (c), 0, 0, 0)
; DI unsigned pk2(float a, float b) { f32x2 v = {a, b}; bf16x2_t r = __builtin_convertvector(v, bf16x2_t); return __builtin_bit_cast(unsigned, r); }
; template <int DQK, bool BAND, int QT> ...
;     ...
;         const float mc = -m[qt] * cc;
;         float ls = 0.f;
; #pragma unroll
;         for (int a = 0; a < 2; ++a) {
; #pragma unroll
;           for (int r = 0; r < 16; ++r) { const float pv = __builtin_amdgcn_exp2f(fmaf(s[a][qt][r], cc, mc)); s[a][qt][r] = pv; ls += pv; }
; #pragma unroll
;           for (int s2 = 0; s2 < 2; ++s2) {
;             u32x4 pk;
;             pk.x = pk2(s[a][qt][8 * s2 + 0], s[a][qt][8 * s2 + 1]);
;             pk.y = pk2(s[a][qt][8 * s2 + 2], s[a][qt][8 * s2 + 3]);
;             pk.z = pk2(s[a][qt][8 * s2 + 4], s[a][qt][8 * s2 + 5]);
;             pk.w = pk2(s[a][qt][8 * s2 + 6], s[a][qt][8 * s2 + 7]);
;             pf[qt][a * 2 + s2] = __builtin_bit_cast(bf16x8, pk);
;           }
;         }
;         l[qt] += ls;
;       }
;       __builtin_amdgcn_s_setprio(0);
;       if (more) lstore(lds + ((it + 1) & 1) * ST);
; #pragma unroll
;       for (int ks = 0; ks < 4; ++ks) {
;         const bf16x8 v0 = *(const bf16x8*)(st + v_rd + ks * 32);
;         const bf16x8 v1 = *(const bf16x8*)(st + v_rd + 32 * LROW + ks * 32);
; #pragma unroll
;         for (int qt = 0; qt < QT; ++qt) {
;           o[0][qt] = MFMA(v0, pf[qt][ks], o[0][qt]);
;           o[1][qt] = MFMA(v1, pf[qt][ks], o[1][qt]);
;         }
;       }
;     } else {
;       if (more) lstore(lds + ((it + 1) & 1) * ST);
;     }
;     __syncthreads();
.Lgqa_nostage:
	v_mul_f32_e32 v106, 0xbe38aa3b, v197
	v_fmamk_f32 v82, v82, 0x3e38aa3b, v106
	v_exp_f32_e32 v107, v82
	v_fmamk_f32 v82, v83, 0x3e38aa3b, v106
	v_cvt_pk_bf16_f32 v99, v108, v109
	v_exp_f32_e32 v108, v82
	v_fmamk_f32 v82, v84, 0x3e38aa3b, v106
	v_exp_f32_e32 v109, v82
	v_fmamk_f32 v82, v85, 0x3e38aa3b, v106
	v_cvt_pk_bf16_f32 v100, v110, v111
	v_exp_f32_e32 v110, v82
	v_fmamk_f32 v82, v86, 0x3e38aa3b, v106
	v_exp_f32_e32 v111, v82
	v_fmamk_f32 v82, v87, 0x3e38aa3b, v106
	v_cvt_pk_bf16_f32 v101, v112, v113
	v_exp_f32_e32 v112, v82
	v_fmamk_f32 v82, v88, 0x3e38aa3b, v106
	v_exp_f32_e32 v113, v82
	v_fmamk_f32 v82, v89, 0x3e38aa3b, v106
	v_exp_f32_e32 v122, v82
	v_fmamk_f32 v82, v90, 0x3e38aa3b, v106
	v_cvt_pk_bf16_f32 v86, v107, v108
	v_add_f32_e32 v107, 0, v107
	v_exp_f32_e32 v90, v82
	v_fmamk_f32 v82, v91, 0x3e38aa3b, v106
	v_add_f32_e32 v107, v108, v107
	v_exp_f32_e32 v91, v82
	v_fmamk_f32 v82, v92, 0x3e38aa3b, v106
	v_add_f32_e32 v107, v109, v107
	v_exp_f32_e32 v92, v82
	v_fmamk_f32 v82, v93, 0x3e38aa3b, v106
	v_add_f32_e32 v107, v110, v107
	v_exp_f32_e32 v93, v82
	v_fmamk_f32 v82, v94, 0x3e38aa3b, v106
	v_add_f32_e32 v107, v111, v107
	v_exp_f32_e32 v94, v82
	v_fmamk_f32 v82, v95, 0x3e38aa3b, v106
	v_add_f32_e32 v107, v112, v107
	v_exp_f32_e32 v95, v82
	v_fmamk_f32 v82, v96, 0x3e38aa3b, v106
	v_add_f32_e32 v107, v113, v107
	v_exp_f32_e32 v96, v82
	v_fmamk_f32 v82, v97, 0x3e38aa3b, v106
	v_add_f32_e32 v107, v122, v107
	v_exp_f32_e32 v97, v82
	v_cvt_pk_bf16_f32 v82, v90, v91
	v_add_f32_e32 v90, v90, v107
	v_add_f32_e32 v90, v91, v90
	v_fmamk_f32 v66, v66, 0x3e38aa3b, v106
	v_add_f32_e32 v90, v92, v90
	v_exp_f32_e32 v91, v66
	v_fmamk_f32 v66, v67, 0x3e38aa3b, v106
	v_cvt_pk_bf16_f32 v83, v92, v93
	v_add_f32_e32 v90, v93, v90
	v_exp_f32_e32 v92, v66
	v_fmamk_f32 v66, v68, 0x3e38aa3b, v106
	v_add_f32_e32 v90, v94, v90
	v_exp_f32_e32 v93, v66
	v_fmamk_f32 v66, v69, 0x3e38aa3b, v106
	v_cvt_pk_bf16_f32 v84, v94, v95
	v_add_f32_e32 v90, v95, v90
	v_exp_f32_e32 v94, v66
	v_fmamk_f32 v66, v70, 0x3e38aa3b, v106
	v_add_f32_e32 v90, v96, v90
	v_exp_f32_e32 v95, v66
	v_fmamk_f32 v66, v71, 0x3e38aa3b, v106
	v_cvt_pk_bf16_f32 v85, v96, v97
	v_add_f32_e32 v90, v97, v90
	v_exp_f32_e32 v96, v66
	v_fmamk_f32 v66, v72, 0x3e38aa3b, v106
	v_exp_f32_e32 v97, v66
	v_fmamk_f32 v66, v73, 0x3e38aa3b, v106
	v_add_f32_e32 v90, v91, v90
	v_exp_f32_e32 v107, v66
	v_fmamk_f32 v66, v74, 0x3e38aa3b, v106
	v_add_f32_e32 v90, v92, v90
	v_exp_f32_e32 v74, v66
	v_fmamk_f32 v66, v75, 0x3e38aa3b, v106
	v_add_f32_e32 v90, v93, v90
	v_exp_f32_e32 v75, v66
	v_fmamk_f32 v66, v76, 0x3e38aa3b, v106
	v_add_f32_e32 v90, v94, v90
	v_exp_f32_e32 v76, v66
	v_fmamk_f32 v66, v77, 0x3e38aa3b, v106
	v_add_f32_e32 v90, v95, v90
	v_exp_f32_e32 v77, v66
	v_fmamk_f32 v66, v78, 0x3e38aa3b, v106
	v_add_f32_e32 v90, v96, v90
	v_exp_f32_e32 v78, v66
	v_fmamk_f32 v66, v79, 0x3e38aa3b, v106
	v_add_f32_e32 v90, v97, v90
	v_exp_f32_e32 v79, v66
	v_fmamk_f32 v66, v80, 0x3e38aa3b, v106
	v_add_f32_e32 v90, v107, v90
	v_exp_f32_e32 v80, v66
	v_cvt_pk_bf16_f32 v66, v74, v75
	v_add_f32_e32 v74, v74, v90
	v_add_f32_e32 v74, v75, v74
	v_fmac_f32_e32 v106, 0x3e38aa3b, v81
	v_add_f32_e32 v74, v76, v74
	v_exp_f32_e32 v81, v106
	v_add_f32_e32 v74, v77, v74
	v_add_f32_e32 v74, v78, v74
	v_add_f32_e32 v74, v79, v74
	v_add_f32_e32 v74, v80, v74
	v_cvt_pk_bf16_f32 v71, v93, v94
	v_add_f32_e32 v74, v81, v74
	v_add3_u32 v94, s7, v183, v0
	v_cvt_pk_bf16_f32 v70, v91, v92
	v_cvt_pk_bf16_f32 v67, v76, v77
	v_cvt_pk_bf16_f32 v68, v78, v79
	v_cvt_pk_bf16_f32 v69, v80, v81
	v_add_f32_e32 v187, v187, v74
	ds_read_b128 v[74:77], v94 offset:13824
	ds_read_b128 v[78:81], v94 offset:9216
	ds_read_b128 v[90:93], v94 offset:9248
	v_cvt_pk_bf16_f32 v119, v207, v208
	v_cvt_pk_bf16_f32 v120, v209, v210
	v_cvt_pk_bf16_f32 v121, v211, v212
	v_cvt_pk_bf16_f32 v87, v109, v110
	v_cvt_pk_bf16_f32 v88, v111, v112
	v_cvt_pk_bf16_f32 v89, v113, v122
	s_waitcnt lgkmcnt(2)
	v_mfma_f32_32x32x16_bf16 v[2:17], v[74:77], v[118:121], v[2:17]
	v_cvt_pk_bf16_f32 v102, v123, v124
	v_cvt_pk_bf16_f32 v103, v125, v126
	v_cvt_pk_bf16_f32 v104, v127, v128
	v_cvt_pk_bf16_f32 v105, v129, v204
	v_cvt_pk_bf16_f32 v72, v95, v96
	v_cvt_pk_bf16_f32 v73, v97, v107
	s_add_i32 s1, s1, 1
	v_mfma_f32_32x32x16_bf16 v[34:49], v[74:77], v[86:89], v[34:49]
	ds_read_b128 v[74:77], v94 offset:13856
	s_add_i32 s6, s6, 64
	v_lshl_add_u64 v[188:189], v[188:189], 0, s[76:77]
	v_lshl_add_u64 v[190:191], v[190:191], 0, s[76:77]
	v_lshl_add_u64 v[192:193], v[192:193], 0, s[88:89]
	v_lshl_add_u64 v[194:195], v[194:195], 0, s[88:89]
	s_cmp_lg_u32 s21, s1
	s_waitcnt lgkmcnt(2)
	v_mfma_f32_32x32x16_bf16 v[50:65], v[78:81], v[86:89], v[50:65]
	v_mfma_f32_32x32x16_bf16 v[18:33], v[78:81], v[118:121], v[18:33]
	s_waitcnt lgkmcnt(1)
	v_mfma_f32_32x32x16_bf16 v[50:65], v[90:93], v[82:85], v[50:65]
	s_waitcnt lgkmcnt(0)
	v_mfma_f32_32x32x16_bf16 v[34:49], v[74:77], v[82:85], v[34:49]
	v_mfma_f32_32x32x16_bf16 v[18:33], v[90:93], v[114:117], v[18:33]
	v_mfma_f32_32x32x16_bf16 v[2:17], v[74:77], v[114:117], v[2:17]
	ds_read_b128 v[74:77], v94 offset:9280
	ds_read_b128 v[78:81], v94 offset:13888
	s_waitcnt lgkmcnt(1)
	v_mfma_f32_32x32x16_bf16 v[50:65], v[74:77], v[70:73], v[50:65]
	s_waitcnt lgkmcnt(0)
	v_mfma_f32_32x32x16_bf16 v[34:49], v[78:81], v[70:73], v[34:49]
	v_mfma_f32_32x32x16_bf16 v[18:33], v[74:77], v[102:105], v[18:33]
	ds_read_b128 v[70:73], v94 offset:9312
	ds_read_b128 v[74:77], v94 offset:13920
	s_waitcnt lgkmcnt(0)
	s_barrier
	v_mfma_f32_32x32x16_bf16 v[2:17], v[78:81], v[102:105], v[2:17]
	v_mfma_f32_32x32x16_bf16 v[50:65], v[70:73], v[66:69], v[50:65]
	v_mfma_f32_32x32x16_bf16 v[34:49], v[74:77], v[66:69], v[34:49]
	v_mfma_f32_32x32x16_bf16 v[18:33], v[70:73], v[98:101], v[18:33]
	v_mfma_f32_32x32x16_bf16 v[2:17], v[74:77], v[98:101], v[2:17]
	s_cbranch_scc0 .LBB0_837

; #define MFMA(a, b, c) __builtin_amdgcn_mfma_f32_32x32x16_bf16((a), (b), (c), 0, 0, 0)
; template <int DQK, bool BAND, int QT> ...
;     ...
;       f32x16 s[2][QT];
; #pragma unroll
;       for (int a = 0; a < 2; ++a)
; #pragma unroll
;         for (int b = 0; b < QT; ++b)
; #pragma unroll
;           for (int r = 0; r < 16; ++r) s[a][b][r] = 0.f;
; #pragma unroll
;       for (int ks = 0; ks < NKS; ++ks) {
;         const bf16x8 k0 = *(const bf16x8*)(st + k_rd + ks * 32);
;         const bf16x8 k1 = *(const bf16x8*)(st + k_rd + 32 * KROW + ks * 32);
; #pragma unroll
;         for (int qt = 0; qt < QT; ++qt) {
;           s[0][qt] = MFMA(k0, qf[qt][ks], s[0][qt]);
;           s[1][qt] = MFMA(k1, qf[qt][ks], s[1][qt]);
;         }
;       }
;       __builtin_amdgcn_s_setprio(3);
;       bf16x8 pf[QT][4];
;       const float cc = BAND ? 1.0f : scale_log2;
;       const float th = BAND ? 8.0f : 8.0f / scale_log2;
; #pragma unroll
;       for (int qt = 0; qt < QT; ++qt) {
;         if (BAND) {
; #pragma unroll
;           for (int a = 0; a < 2; ++a)
; #pragma unroll
;             for (int r = 0; r < 16; ++r) {
;               const int kidx = kt + 32 * a + (r & 7) + 8 * h + 16 * (r >> 3);
;               const int rel = kidx - (qw0 + qt * 32 + ql);
;               const bool ok = (rel >= -64) && (rel <= 64);
;               const int bi = ok ? rel + 64 : 0;
;               s[a][qt][r] = ok ? fmaf(s[a][qt][r], scale_log2, bias_l[bi]) : -1e30f;
;             }
;         }
;         float mx = s[0][qt][0];
; #pragma unroll
;         for (int r = 1; r < 16; ++r) mx = fmaxf(mx, s[0][qt][r]);
; #pragma unroll
;         for (int r = 0; r < 16; ++r) mx = fmaxf(mx, s[1][qt][r]);
;         mx = fmaxf(mx, __shfl_xor(mx, 32));
;         if (__builtin_amdgcn_ballot_w64(mx > m[qt] + th) != 0) {
;           const float mn = fmaxf(m[qt], mx);
;           const float alpha = __builtin_amdgcn_exp2f((m[qt] - mn) * cc);
;           m[qt] = mn;
;           l[qt] *= alpha;
; #pragma unroll
;           for (int r = 0; r < 16; ++r) { o[0][qt][r] *= alpha; o[1][qt][r] *= alpha; }
;         }
.LBB0_831:
	s_bitcmp1_b32 s1, 0
	s_cselect_b32 s7, 0x4800, 0
	s_add_i32 s7, s7, 0
	v_add3_u32 v203, s7, v185, v0
	ds_read_b128 v[98:101], v203 offset:4608
	ds_read_b128 v[102:105], v203
	ds_read_b128 v[206:209], v203 offset:32
	ds_read_b128 v[210:213], v203 offset:4640
	s_waitcnt lgkmcnt(3)
	v_mfma_f32_32x32x16_bf16 v[66:81], v[98:101], v[146:149], 0
	s_waitcnt lgkmcnt(2)
	v_mfma_f32_32x32x16_bf16 v[82:97], v[102:105], v[146:149], 0
	v_mfma_f32_32x32x16_bf16 v[114:129], v[102:105], v[162:165], 0
	v_mfma_f32_32x32x16_bf16 v[98:113], v[98:101], v[162:165], 0
	s_waitcnt lgkmcnt(1)
	v_mfma_f32_32x32x16_bf16 v[82:97], v[206:209], v[150:153], v[82:97]
	s_waitcnt lgkmcnt(0)
	v_mfma_f32_32x32x16_bf16 v[66:81], v[210:213], v[150:153], v[66:81]
	v_mfma_f32_32x32x16_bf16 v[114:129], v[206:209], v[166:169], v[114:129]
	v_mfma_f32_32x32x16_bf16 v[98:113], v[210:213], v[166:169], v[98:113]
	ds_read_b128 v[206:209], v203 offset:64
	ds_read_b128 v[210:213], v203 offset:4672
	s_waitcnt lgkmcnt(1)
	v_mfma_f32_32x32x16_bf16 v[82:97], v[206:209], v[154:157], v[82:97]
	s_waitcnt lgkmcnt(0)
	v_mfma_f32_32x32x16_bf16 v[66:81], v[210:213], v[154:157], v[66:81]
	v_mfma_f32_32x32x16_bf16 v[114:129], v[206:209], v[170:173], v[114:129]
	v_mfma_f32_32x32x16_bf16 v[98:113], v[210:213], v[170:173], v[98:113]
	ds_read_b128 v[206:209], v203 offset:96
	ds_read_b128 v[210:213], v203 offset:4704
	s_waitcnt lgkmcnt(1)
	v_mfma_f32_32x32x16_bf16 v[82:97], v[206:209], v[158:161], v[82:97]
	s_waitcnt lgkmcnt(0)
	v_mfma_f32_32x32x16_bf16 v[66:81], v[210:213], v[158:161], v[66:81]
	v_mfma_f32_32x32x16_bf16 v[114:129], v[206:209], v[174:177], v[114:129]
	v_mfma_f32_32x32x16_bf16 v[98:113], v[210:213], v[174:177], v[98:113]
	s_setprio 3
	s_nop 6
	v_max_f32_e32 v203, v82, v83
	v_max3_f32 v203, v203, v84, v85
	v_max3_f32 v203, v203, v86, v87
	v_max3_f32 v203, v203, v88, v89
	v_max3_f32 v203, v203, v90, v91
	v_max3_f32 v203, v203, v92, v93
	v_max3_f32 v203, v203, v94, v95
	v_max3_f32 v203, v203, v96, v97
	v_max3_f32 v203, v203, v66, v67
	v_max3_f32 v203, v203, v68, v69
	v_max3_f32 v203, v203, v70, v71
	v_max3_f32 v203, v203, v72, v73
	v_max3_f32 v203, v203, v74, v75
	v_max3_f32 v203, v203, v76, v77
	v_max3_f32 v203, v203, v78, v79
	v_max3_f32 v203, v203, v80, v81
	v_add_f32_e32 v204, 0x42317218, v197
	v_cmp_gt_f32_e32 vcc, v203, v204
	s_cbranch_vccz .LBB0_833
	ds_bpermute_b32 v204, v179, v203
	s_waitcnt lgkmcnt(0)
	v_max_f32_e32 v204, v204, v204
	v_max_f32_e32 v203, v203, v204
	v_max_f32_e32 v203, v203, v203
	v_max_f32_e32 v204, v197, v197
	v_max_f32_e32 v203, v204, v203
	v_sub_f32_e32 v197, v197, v203
	v_mul_f32_e32 v197, 0x3e38aa3b, v197
	v_exp_f32_e32 v204, v197
	v_mov_b32_e32 v197, v203
	v_mul_f32_e32 v187, v187, v204
	v_pk_mul_f32 v[64:65], v[64:65], v[204:205] op_sel_hi:[1,0]
	v_pk_mul_f32 v[62:63], v[62:63], v[204:205] op_sel_hi:[1,0]
	v_pk_mul_f32 v[60:61], v[60:61], v[204:205] op_sel_hi:[1,0]
	v_pk_mul_f32 v[58:59], v[58:59], v[204:205] op_sel_hi:[1,0]
	v_pk_mul_f32 v[56:57], v[56:57], v[204:205] op_sel_hi:[1,0]
	v_pk_mul_f32 v[54:55], v[54:55], v[204:205] op_sel_hi:[1,0]
	v_pk_mul_f32 v[52:53], v[52:53], v[204:205] op_sel_hi:[1,0]
	v_pk_mul_f32 v[50:51], v[50:51], v[204:205] op_sel_hi:[1,0]
	v_pk_mul_f32 v[48:49], v[48:49], v[204:205] op_sel_hi:[1,0]
	v_pk_mul_f32 v[46:47], v[46:47], v[204:205] op_sel_hi:[1,0]
	v_pk_mul_f32 v[44:45], v[44:45], v[204:205] op_sel_hi:[1,0]
	v_pk_mul_f32 v[42:43], v[42:43], v[204:205] op_sel_hi:[1,0]
	v_pk_mul_f32 v[40:41], v[40:41], v[204:205] op_sel_hi:[1,0]
	v_pk_mul_f32 v[38:39], v[38:39], v[204:205] op_sel_hi:[1,0]
	v_pk_mul_f32 v[36:37], v[36:37], v[204:205] op_sel_hi:[1,0]
	v_pk_mul_f32 v[34:35], v[34:35], v[204:205] op_sel_hi:[1,0]
.LBB0_833:
	v_max_f32_e32 v203, v114, v115
	v_max3_f32 v203, v203, v116, v117
	v_max3_f32 v203, v203, v118, v119
	v_max3_f32 v203, v203, v120, v121
	v_max3_f32 v203, v203, v122, v123
	v_max3_f32 v203, v203, v124, v125
	v_max3_f32 v203, v203, v126, v127
	v_max3_f32 v203, v203, v128, v129
	v_max3_f32 v203, v203, v98, v99
	v_max3_f32 v203, v203, v100, v101
	v_max3_f32 v203, v203, v102, v103
	v_max3_f32 v203, v203, v104, v105
	v_max3_f32 v203, v203, v106, v107
	v_max3_f32 v203, v203, v108, v109
	v_max3_f32 v203, v203, v110, v111
	v_max3_f32 v203, v203, v112, v113
	v_add_f32_e32 v204, 0x42317218, v202
	v_cmp_gt_f32_e32 vcc, v203, v204
	s_cbranch_vccz .LBB0_835
	ds_bpermute_b32 v204, v179, v203
	s_waitcnt lgkmcnt(0)
	v_max_f32_e32 v204, v204, v204
	v_max_f32_e32 v203, v203, v204
	v_max_f32_e32 v203, v203, v203
	v_max_f32_e32 v204, v202, v202
	v_max_f32_e32 v203, v204, v203
	v_sub_f32_e32 v202, v202, v203
	v_mul_f32_e32 v202, 0x3e38aa3b, v202
	v_exp_f32_e32 v202, v202
	s_nop 0
	v_mul_f32_e32 v181, v181, v202
	v_pk_mul_f32 v[32:33], v[32:33], v[202:203] op_sel_hi:[1,0]
	v_pk_mul_f32 v[30:31], v[30:31], v[202:203] op_sel_hi:[1,0]
	v_pk_mul_f32 v[28:29], v[28:29], v[202:203] op_sel_hi:[1,0]
	v_pk_mul_f32 v[26:27], v[26:27], v[202:203] op_sel_hi:[1,0]
	v_pk_mul_f32 v[24:25], v[24:25], v[202:203] op_sel_hi:[1,0]
	v_pk_mul_f32 v[22:23], v[22:23], v[202:203] op_sel_hi:[1,0]
	v_pk_mul_f32 v[20:21], v[20:21], v[202:203] op_sel_hi:[1,0]
	v_pk_mul_f32 v[18:19], v[18:19], v[202:203] op_sel_hi:[1,0]
	v_pk_mul_f32 v[16:17], v[16:17], v[202:203] op_sel_hi:[1,0]
	v_pk_mul_f32 v[14:15], v[14:15], v[202:203] op_sel_hi:[1,0]
	v_pk_mul_f32 v[12:13], v[12:13], v[202:203] op_sel_hi:[1,0]
	v_pk_mul_f32 v[10:11], v[10:11], v[202:203] op_sel_hi:[1,0]
	v_pk_mul_f32 v[8:9], v[8:9], v[202:203] op_sel_hi:[1,0]
	v_pk_mul_f32 v[6:7], v[6:7], v[202:203] op_sel_hi:[1,0]
	v_pk_mul_f32 v[4:5], v[4:5], v[202:203] op_sel_hi:[1,0]
	v_pk_mul_f32 v[2:3], v[2:3], v[202:203] op_sel_hi:[1,0]
	v_mov_b32_e32 v202, v203
.LBB0_835:
	s_setprio 0
	s_branch .LBB0_828

; DI int tid_() { int t = threadIdx.x; asm volatile("" : "+v"(t)); return t; }
; template <int DQK, bool BAND, int QT> ...
;     ...
;   const int tid = tid_(), lane = tid & 63, w = tid >> 6, h = lane >> 5, ql = lane & 31;
;   float* bias_l = (float*)(lds + 2 * ST);
;   if (BAND) { if (tid < 129) bias_l[tid] = bias_g[tid]; }
;   bf16x8 qf[QT][NKS];
; #pragma unroll
;   for (int qt = 0; qt < QT; ++qt)
; #pragma unroll
;     for (int ks = 0; ks < NKS; ++ks) qf[qt][ks] = *(const bf16x8*)(Q + (size_t)(w * WQ + qt * 32 + ql) * DQK + ks * 16 + h * 8);
;   f32x16 o[2][QT];
; #pragma unroll
;   for (int a = 0; a < 2; ++a)
; #pragma unroll
;     for (int b = 0; b < QT; ++b)
; #pragma unroll
;       for (int r = 0; r < 16; ++r) o[a][b][r] = 0.f;
;   float m[QT], l[QT];
; #pragma unroll
;   for (int qt = 0; qt < QT; ++qt) { m[qt] = -1e30f; l[qt] = 0.f; }
;   u32x4 rk[NKL], rv[2];
;   const int vrow0 = tid >> 3, vch = tid & 7;
;   unsigned klds[NKL];
; #pragma unroll
;   for (int i = 0; i < NKL; ++i) { const int idx = tid + i * 256, kr = idx / KV4, kc = idx - kr * KV4; klds[i] = kr * KROW + kc * 16; }
;   const unsigned koff0 = (unsigned)tid * 16u;
;   const unsigned voff0 = (unsigned)(vrow0 * ldv + vch * 8) * 2u, vstep = (unsigned)(32 * ldv) * 2u;
;   const unsigned vlds0 = KST + vrow0 * LROW + vch * 16;
;   auto gload = [&](int kt) {
;     const char* kb = (const char*)Kp + (size_t)kt * (DQK * 2);
;     const char* vb = (const char*)Vt + (size_t)kt * 2;
; #pragma unroll
;     for (int i = 0; i < NKL; ++i) rk[i] = *(const u32x4*)(kb + (koff0 + i * 4096u));
; #pragma unroll
;     for (int i = 0; i < 2; ++i) rv[i] = *(const u32x4*)(vb + (voff0 + i * vstep));
;   };
;   auto lstore = [&](char* st) {
; #pragma unroll
;     for (int i = 0; i < NKL; ++i) *(u32x4*)(st + klds[i]) = rk[i];
; #pragma unroll
;     for (int i = 0; i < 2; ++i) *(u32x4*)(st + vlds0 + i * 32 * LROW) = rv[i];
;   };
;   gload(kbeg);
;   lstore(lds);
;   __syncthreads();
;   const int pr = (ql & ~12) | ((ql & 4) << 1) | ((ql & 8) >> 1);
;   const int k_rd = pr * KROW + h * 16;
;   const int v_rd = KST + ql * LROW + h * 16;
.LBB0_839:
	s_andn2_b64 vcc, exec, s[0:1]
	s_cbranch_vccnz .LBB0_664
	s_abs_i32 s0, s25
	v_readlane_b32 s1, v248, 3
	s_mul_hi_u32 s1, s0, s1
	v_readlane_b32 s4, v248, 2
	s_mul_i32 s2, s1, s4
	s_sub_i32 s0, s0, s2
	s_ashr_i32 s7, s25, 31
	s_add_i32 s2, s1, 1
	s_sub_i32 s3, s0, s4
	s_cmp_ge_u32 s0, s4
	s_cselect_b32 s1, s2, s1
	s_cselect_b32 s0, s3, s0
	s_add_i32 s2, s1, 1
	s_cmp_ge_u32 s0, s4
	s_cselect_b32 s0, s2, s1
	s_xor_b32 s38, s0, s7
	s_sub_i32 s0, s38, s7
	s_lshl_b32 s1, s0, s60
	s_lshl_b32 s2, s0, 3
	v_readlane_b32 s40, v249, 31
	s_sub_i32 s1, s25, s1
	s_or_b32 s26, s2, s40
	s_ashr_i32 s27, s26, 31
	s_lshl_b32 s4, s1, 8
	s_lshl_b64 s[34:35], s[26:27], s20
	s_ashr_i32 s5, s4, 31
	s_add_u32 s1, s34, s4
	s_addc_u32 s2, s35, s5
	s_mulk_i32 s2, 0xc0
	s_mul_hi_u32 s3, s1, 0xc0
	s_add_i32 s3, s3, s2
	s_mulk_i32 s1, 0xc0
	v_readlane_b32 s42, v250, 40
	v_readlane_b32 s43, v250, 41
	s_add_u32 s2, s42, s1
	s_mul_i32 s1, s35, 0xc0
	s_mul_hi_u32 s6, s34, 0xc0
	s_addc_u32 s3, s43, s3
	s_add_i32 s25, s6, s1
	s_mul_i32 s39, s34, 0xc0
	v_readlane_b32 s34, v250, 38
	v_readlane_b32 s35, v250, 39
	s_add_u32 s34, s34, s39
	v_mov_b32_e32 v2, v199
	s_addc_u32 s35, s35, s25
	v_readlane_b32 s1, v249, 61
	v_lshlrev_b32_e32 v4, 4, v2
	global_load_dwordx4 v[130:133], v4, s[34:35]
	v_add_u32_e32 v8, 0x1000, v4
	global_load_dwordx4 v[134:137], v8, s[34:35]
	s_mul_hi_i32 s27, s26, s1
	s_mul_i32 s26, s26, s1
	s_lshl_b64 s[26:27], s[26:27], 1
	v_readlane_b32 s42, v250, 36
	v_ashrrev_i32_e32 v3, 3, v2
	v_readlane_b32 s6, v249, 63
	v_readlane_b32 s43, v250, 37
	s_add_u32 s26, s42, s26
	v_and_b32_e32 v6, 0x70, v4
	v_mul_lo_u32 v0, v3, s6
	s_addc_u32 s27, s43, s27
	v_add_u32_e32 v10, 0x2000, v4
	v_or_b32_e32 v12, v6, v0
	v_bfe_u32 v230, v2, 5, 1
	global_load_dwordx4 v[138:141], v10, s[34:35]
	v_add_u32_e32 v14, s1, v12
	global_load_dwordx4 v[146:149], v12, s[26:27]
	global_load_dwordx4 v[170:173], v14, s[26:27]
	v_lshlrev_b32_e32 v0, 4, v230
	v_and_b32_e32 v204, 0xffffffdf, v2
	v_lshl_add_u64 v[16:17], s[2:3], 0, v[0:1]
	s_movk_i32 s1, 0xc0
	v_or_b32_e32 v202, 32, v2
	v_mad_i64_i32 v[18:19], s[2:3], v204, s1, v[16:17]
	v_mad_i64_i32 v[16:17], s[2:3], v202, s1, v[16:17]
	global_load_dwordx4 v[142:145], v[18:19], off
	global_load_dwordx4 v[150:153], v[18:19], off offset:32
	global_load_dwordx4 v[154:157], v[18:19], off offset:64
	global_load_dwordx4 v[158:161], v[18:19], off offset:96
	global_load_dwordx4 v[162:165], v[18:19], off offset:128
	global_load_dwordx4 v[166:169], v[18:19], off offset:160
	global_load_dwordx4 v[174:177], v[16:17], off
	global_load_dwordx4 v[178:181], v[16:17], off offset:32
	global_load_dwordx4 v[182:185], v[16:17], off offset:64
	global_load_dwordx4 v[186:189], v[16:17], off offset:96
	global_load_dwordx4 v[190:193], v[16:17], off offset:128
	global_load_dwordx4 v[194:197], v[16:17], off offset:160
	s_mov_b32 s1, 0x2aaaaaab
	v_mul_hi_i32 v5, v2, s1
	v_lshrrev_b32_e32 v7, 31, v5
	v_ashrrev_i32_e32 v5, 1, v5
	v_add_u32_e32 v5, v5, v7
	s_movk_i32 s6, 0xd0
	v_mad_u64_u32 v[16:17], s[2:3], v5, -12, v[2:3]
	v_mul_lo_u32 v5, v5, s6
	v_lshl_add_u32 v231, v16, 4, v5
	v_add_u32_e32 v16, 0x100, v2
	v_mul_hi_i32 v5, v16, s1
	v_lshrrev_b32_e32 v7, 31, v5
	v_ashrrev_i32_e32 v5, 1, v5
	v_add_u32_e32 v5, v5, v7
	v_mad_u64_u32 v[16:17], s[2:3], v5, -12, v[16:17]
	v_mul_lo_u32 v5, v5, s6
	v_lshl_add_u32 v232, v16, 4, v5
	v_add_u32_e32 v16, 0x200, v2
	v_mul_hi_i32 v5, v16, s1
	v_lshrrev_b32_e32 v7, 31, v5
	v_ashrrev_i32_e32 v5, 1, v5
	v_add_u32_e32 v5, v5, v7
	v_mad_u64_u32 v[16:17], s[2:3], v5, -12, v[16:17]
	v_mul_lo_u32 v5, v5, s6
	v_add_u32_e32 v7, 0, v231
	v_lshl_add_u32 v233, v16, 4, v5
	v_mov_b32_e32 v13, v1
	v_mov_b32_e32 v15, v1
	v_cmp_lt_i32_e32 vcc, v221, v220
	v_mov_b32_e32 v5, v1
	v_mov_b32_e32 v9, v1
	v_mov_b32_e32 v11, v1
	v_mov_b32_e32 v50, v1
	v_mov_b32_e32 v51, v1
	v_mov_b32_e32 v52, v1
	v_mov_b32_e32 v53, v1
	v_mov_b32_e32 v54, v1
	v_mov_b32_e32 v55, v1
	v_mov_b32_e32 v56, v1
	v_mov_b32_e32 v57, v1
	v_mov_b32_e32 v58, v1
	v_mov_b32_e32 v59, v1
	v_mov_b32_e32 v60, v1
	v_mov_b32_e32 v61, v1
	v_mov_b32_e32 v62, v1
	v_mov_b32_e32 v63, v1
	s_waitcnt vmcnt(16)
	ds_write_b128 v7, v[130:133]
	v_add_u32_e32 v7, 0, v232
	s_waitcnt vmcnt(15)
	ds_write_b128 v7, v[134:137]
	v_add_u32_e32 v7, 0, v233
	v_mad_u64_u32 v[206:207], s[2:3], v3, s16, v[6:7]
	s_lshl_b32 s2, s38, 3
	s_or_b32 s2, s40, s2
	s_lshl_b32 s3, s7, 3
	v_add_u32_e32 v3, 0, v206
	s_sub_i32 s2, s2, s3
	v_readlane_b32 s7, v248, 4
	s_mul_hi_i32 s3, s7, s2
	s_mul_i32 s2, s7, s2
	v_lshlrev_b32_e32 v6, 1, v2
	s_add_u32 s2, s2, 0x10d35980
	v_and_b32_e32 v6, 8, v6
	s_waitcnt vmcnt(14)
	ds_write_b128 v7, v[138:141]
	s_waitcnt vmcnt(13)
	ds_write_b128 v3, v[146:149] offset:13312
	s_waitcnt vmcnt(12)
	ds_write_b128 v3, v[170:173] offset:17920
	v_and_b32_e32 v3, 31, v2
	v_mul_u32_u24_e32 v234, 0x90, v3
	v_and_b32_e32 v3, 19, v2
	v_lshrrev_b32_e32 v2, 1, v2
	v_and_b32_e32 v2, 4, v2
	s_addc_u32 s3, s3, 0
	v_or3_b32 v2, v3, v6, v2
	v_lshl_add_u64 v[208:209], s[2:3], 0, v[12:13]
	v_lshl_add_u64 v[210:211], s[2:3], 0, v[14:15]
	s_add_u32 s2, s39, 0xf538900
	v_mul_u32_u24_e32 v235, 0xd0, v2
	v_cndmask_b32_e32 v2, v219, v221, vcc
	s_addc_u32 s3, s25, 0
	v_lshlrev_b32_e32 v203, 2, v2
	v_lshl_add_u64 v[212:213], s[2:3], 0, v[4:5]
	v_lshl_add_u64 v[214:215], s[2:3], 0, v[8:9]
	v_lshl_add_u64 v[216:217], s[2:3], 0, v[10:11]
	v_mov_b32_e32 v64, v1
	v_mov_b32_e32 v65, v1
	v_mov_b64_e32 v[18:19], v[50:51]
	v_mov_b64_e32 v[34:35], v[50:51]
	v_mov_b64_e32 v[2:3], v[50:51]
	s_mov_b32 s1, 0
	s_mov_b32 s6, 64
	v_mov_b32_e32 v237, 0xf149f2ca
	v_mov_b32_e32 v236, 0
	v_mov_b32_e32 v207, 0
	v_mov_b32_e32 v238, 0xf149f2ca
	v_mov_b64_e32 v[20:21], v[52:53]
	v_mov_b64_e32 v[22:23], v[54:55]
	v_mov_b64_e32 v[24:25], v[56:57]
	v_mov_b64_e32 v[26:27], v[58:59]
	v_mov_b64_e32 v[28:29], v[60:61]
	v_mov_b64_e32 v[30:31], v[62:63]
	v_mov_b64_e32 v[32:33], v[64:65]
	v_mov_b64_e32 v[36:37], v[52:53]
	v_mov_b64_e32 v[38:39], v[54:55]
	v_mov_b64_e32 v[40:41], v[56:57]
	v_mov_b64_e32 v[42:43], v[58:59]
	v_mov_b64_e32 v[44:45], v[60:61]
	v_mov_b64_e32 v[46:47], v[62:63]
	v_mov_b64_e32 v[48:49], v[64:65]
	v_mov_b64_e32 v[4:5], v[52:53]
	v_mov_b64_e32 v[6:7], v[54:55]
	v_mov_b64_e32 v[8:9], v[56:57]
	v_mov_b64_e32 v[10:11], v[58:59]
	v_mov_b64_e32 v[12:13], v[60:61]
	v_mov_b64_e32 v[14:15], v[62:63]
	v_mov_b64_e32 v[16:17], v[64:65]
	s_waitcnt vmcnt(0) lgkmcnt(0)
	s_barrier
	s_branch .LBB0_842
; DI unsigned pk2(float a, float b) { f32x2 v = {a, b}; bf16x2_t r = __builtin_convertvector(v, bf16x2_t); return __builtin_bit_cast(unsigned, r); }
; template <int DQK, bool BAND, int QT> ...
;     ...
;   auto lstore = [&](char* st) {
; #pragma unroll
;     for (int i = 0; i < NKL; ++i) *(u32x4*)(st + klds[i]) = rk[i];
; #pragma unroll
;     for (int i = 0; i < 2; ++i) *(u32x4*)(st + vlds0 + i * 32 * LROW) = rv[i];
;   };
;     ...
;         const float mc = -m[qt] * cc;
;         float ls = 0.f;
; #pragma unroll
;         for (int a = 0; a < 2; ++a) {
; #pragma unroll
;           for (int r = 0; r < 16; ++r) { const float pv = __builtin_amdgcn_exp2f(fmaf(s[a][qt][r], cc, mc)); s[a][qt][r] = pv; ls += pv; }
; #pragma unroll
;           for (int s2 = 0; s2 < 2; ++s2) {
;             u32x4 pk;
;             pk.x = pk2(s[a][qt][8 * s2 + 0], s[a][qt][8 * s2 + 1]);
;             pk.y = pk2(s[a][qt][8 * s2 + 2], s[a][qt][8 * s2 + 3]);
;             pk.z = pk2(s[a][qt][8 * s2 + 4], s[a][qt][8 * s2 + 5]);
;             pk.w = pk2(s[a][qt][8 * s2 + 6], s[a][qt][8 * s2 + 7]);
;             pf[qt][a * 2 + s2] = __builtin_bit_cast(bf16x8, pk);
;           }
;         }
;         l[qt] += ls;
.LBB0_841:
	v_mul_f32_e32 v239, 0xbe16c740, v238
	v_fmamk_f32 v114, v114, 0x3e16c740, v239
	v_exp_f32_e32 v240, v114
	v_fmamk_f32 v114, v115, 0x3e16c740, v239
	v_exp_f32_e32 v241, v114
	v_fmamk_f32 v114, v116, 0x3e16c740, v239
	v_exp_f32_e32 v242, v114
	v_fmamk_f32 v114, v117, 0x3e16c740, v239
	v_exp_f32_e32 v243, v114
	v_fmamk_f32 v114, v118, 0x3e16c740, v239
	v_exp_f32_e32 v244, v114
	v_fmamk_f32 v114, v119, 0x3e16c740, v239
	v_exp_f32_e32 v245, v114
	v_fmamk_f32 v114, v120, 0x3e16c740, v239
	v_exp_f32_e32 v246, v114
	v_fmamk_f32 v114, v121, 0x3e16c740, v239
	v_exp_f32_e32 v247, v114
	v_fmamk_f32 v114, v122, 0x3e16c740, v239
	v_cvt_pk_bf16_f32 v118, v240, v241
	v_add_f32_e32 v240, 0, v240
	v_exp_f32_e32 v122, v114
	v_fmamk_f32 v114, v123, 0x3e16c740, v239
	v_add_f32_e32 v240, v241, v240
	v_exp_f32_e32 v123, v114
	v_fmamk_f32 v114, v124, 0x3e16c740, v239
	v_add_f32_e32 v240, v242, v240
	v_exp_f32_e32 v124, v114
	v_fmamk_f32 v114, v125, 0x3e16c740, v239
	v_add_f32_e32 v240, v243, v240
	v_exp_f32_e32 v125, v114
	v_fmamk_f32 v114, v126, 0x3e16c740, v239
	v_add_f32_e32 v240, v244, v240
	v_exp_f32_e32 v126, v114
	v_fmamk_f32 v114, v127, 0x3e16c740, v239
	v_add_f32_e32 v240, v245, v240
	v_exp_f32_e32 v127, v114
	v_fmamk_f32 v114, v128, 0x3e16c740, v239
	v_add_f32_e32 v240, v246, v240
	v_exp_f32_e32 v128, v114
	v_fmamk_f32 v114, v129, 0x3e16c740, v239
	v_add_f32_e32 v240, v247, v240
	v_exp_f32_e32 v129, v114
	v_cvt_pk_bf16_f32 v114, v122, v123
	v_add_f32_e32 v122, v122, v240
	v_add_f32_e32 v122, v123, v122
	v_fmamk_f32 v98, v98, 0x3e16c740, v239
	v_add_f32_e32 v122, v124, v122
	v_exp_f32_e32 v123, v98
	v_fmamk_f32 v98, v99, 0x3e16c740, v239
	v_cvt_pk_bf16_f32 v115, v124, v125
	v_add_f32_e32 v122, v125, v122
	v_exp_f32_e32 v124, v98
	v_fmamk_f32 v98, v100, 0x3e16c740, v239
	v_add_f32_e32 v122, v126, v122
	v_exp_f32_e32 v125, v98
	v_fmamk_f32 v98, v101, 0x3e16c740, v239
	v_cvt_pk_bf16_f32 v116, v126, v127
	v_add_f32_e32 v122, v127, v122
	v_exp_f32_e32 v126, v98
	v_fmamk_f32 v98, v102, 0x3e16c740, v239
	v_add_f32_e32 v122, v128, v122
	v_exp_f32_e32 v127, v98
	v_fmamk_f32 v98, v103, 0x3e16c740, v239
	v_cvt_pk_bf16_f32 v117, v128, v129
	v_add_f32_e32 v122, v129, v122
	v_exp_f32_e32 v128, v98
	v_fmamk_f32 v98, v104, 0x3e16c740, v239
	v_exp_f32_e32 v129, v98
	v_fmamk_f32 v98, v105, 0x3e16c740, v239
	v_add_f32_e32 v122, v123, v122
	v_exp_f32_e32 v240, v98
	v_fmamk_f32 v98, v106, 0x3e16c740, v239
	v_add_f32_e32 v122, v124, v122
	v_exp_f32_e32 v106, v98
	v_fmamk_f32 v98, v107, 0x3e16c740, v239
	v_add_f32_e32 v122, v125, v122
	v_exp_f32_e32 v107, v98
	v_fmamk_f32 v98, v108, 0x3e16c740, v239
	v_add_f32_e32 v122, v126, v122
	v_exp_f32_e32 v108, v98
	v_fmamk_f32 v98, v109, 0x3e16c740, v239
	v_add_f32_e32 v122, v127, v122
	v_exp_f32_e32 v109, v98
	v_fmamk_f32 v98, v110, 0x3e16c740, v239
	v_add_f32_e32 v122, v128, v122
	v_exp_f32_e32 v110, v98
	v_fmamk_f32 v98, v111, 0x3e16c740, v239
	v_add_f32_e32 v122, v129, v122
	v_exp_f32_e32 v111, v98
	v_fmamk_f32 v98, v112, 0x3e16c740, v239
	v_add_f32_e32 v122, v240, v122
	v_exp_f32_e32 v112, v98
	v_cvt_pk_bf16_f32 v98, v106, v107
	v_add_f32_e32 v106, v106, v122
	v_add_f32_e32 v106, v107, v106
	v_fmac_f32_e32 v239, 0x3e16c740, v113
	v_add_f32_e32 v106, v108, v106
	v_exp_f32_e32 v113, v239
	v_add_f32_e32 v106, v109, v106
	v_add_f32_e32 v106, v110, v106
	v_add_f32_e32 v106, v111, v106
	v_add_f32_e32 v106, v112, v106
	v_add_f32_e32 v106, v113, v106
	v_add_f32_e32 v207, v207, v106
	s_andn2_b64 vcc, exec, s[2:3]
	s_cbranch_vccnz .Lmla_nostage
	s_andn2_b32 s2, 1, s1
	s_mulk_i32 s2, 0x5800
	v_add_u32_e32 v239, s2, v231
	s_waitcnt vmcnt(4)
	ds_write_b128 v239, v[130:133]
	v_add_u32_e32 v239, s2, v232
	s_waitcnt vmcnt(3)
	ds_write_b128 v239, v[134:137]
	v_add_u32_e32 v239, s2, v233
	s_waitcnt vmcnt(2)
	ds_write_b128 v239, v[138:141]
	v_add_u32_e32 v239, s2, v206
	s_waitcnt vmcnt(1)
	ds_write_b128 v239, v[146:149] offset:13312
	s_waitcnt vmcnt(0)
	ds_write_b128 v239, v[170:173] offset:17920
; #define MFMA(a, b, c) __builtin_amdgcn_mfma_f32_32x32x16_bf16((a), (b), (c), 0, 0, 0)
; DI unsigned pk2(float a, float b) { f32x2 v = {a, b}; bf16x2_t r = __builtin_convertvector(v, bf16x2_t); return __builtin_bit_cast(unsigned, r); }
; template <int DQK, bool BAND, int QT> ...
;     ...
;         const float mc = -m[qt] * cc;
;         float ls = 0.f;
; #pragma unroll
;         for (int a = 0; a < 2; ++a) {
; #pragma unroll
;           for (int r = 0; r < 16; ++r) { const float pv = __builtin_amdgcn_exp2f(fmaf(s[a][qt][r], cc, mc)); s[a][qt][r] = pv; ls += pv; }
; #pragma unroll
;           for (int s2 = 0; s2 < 2; ++s2) {
;             u32x4 pk;
;             pk.x = pk2(s[a][qt][8 * s2 + 0], s[a][qt][8 * s2 + 1]);
;             pk.y = pk2(s[a][qt][8 * s2 + 2], s[a][qt][8 * s2 + 3]);
;             pk.z = pk2(s[a][qt][8 * s2 + 4], s[a][qt][8 * s2 + 5]);
;             pk.w = pk2(s[a][qt][8 * s2 + 6], s[a][qt][8 * s2 + 7]);
;             pf[qt][a * 2 + s2] = __builtin_bit_cast(bf16x8, pk);
;           }
;         }
;         l[qt] += ls;
;       }
;       __builtin_amdgcn_s_setprio(0);
;       if (more) lstore(lds + ((it + 1) & 1) * ST);
; #pragma unroll
;       for (int ks = 0; ks < 4; ++ks) {
;         const bf16x8 v0 = *(const bf16x8*)(st + v_rd + ks * 32);
;         const bf16x8 v1 = *(const bf16x8*)(st + v_rd + 32 * LROW + ks * 32);
; #pragma unroll
;         for (int qt = 0; qt < QT; ++qt) {
;           o[0][qt] = MFMA(v0, pf[qt][ks], o[0][qt]);
;           o[1][qt] = MFMA(v1, pf[qt][ks], o[1][qt]);
;         }
;       }
;     } else {
;       if (more) lstore(lds + ((it + 1) & 1) * ST);
;     }
;     __syncthreads();
.Lmla_nostage:
	v_mul_f32_e32 v106, 0xbe16c740, v237
	v_fmamk_f32 v82, v82, 0x3e16c740, v106
	v_exp_f32_e32 v107, v82
	v_fmamk_f32 v82, v83, 0x3e16c740, v106
	v_cvt_pk_bf16_f32 v99, v108, v109
	v_exp_f32_e32 v108, v82
	v_fmamk_f32 v82, v84, 0x3e16c740, v106
	v_exp_f32_e32 v109, v82
	v_fmamk_f32 v82, v85, 0x3e16c740, v106
	v_cvt_pk_bf16_f32 v100, v110, v111
	v_exp_f32_e32 v110, v82
	v_fmamk_f32 v82, v86, 0x3e16c740, v106
	v_exp_f32_e32 v111, v82
	v_fmamk_f32 v82, v87, 0x3e16c740, v106
	v_cvt_pk_bf16_f32 v101, v112, v113
	v_exp_f32_e32 v112, v82
	v_fmamk_f32 v82, v88, 0x3e16c740, v106
	v_exp_f32_e32 v113, v82
	v_fmamk_f32 v82, v89, 0x3e16c740, v106
	v_exp_f32_e32 v122, v82
	v_fmamk_f32 v82, v90, 0x3e16c740, v106
	v_cvt_pk_bf16_f32 v86, v107, v108
	v_add_f32_e32 v107, 0, v107
	v_exp_f32_e32 v90, v82
	v_fmamk_f32 v82, v91, 0x3e16c740, v106
	v_add_f32_e32 v107, v108, v107
	v_exp_f32_e32 v91, v82
	v_fmamk_f32 v82, v92, 0x3e16c740, v106
	v_add_f32_e32 v107, v109, v107
	v_exp_f32_e32 v92, v82
	v_fmamk_f32 v82, v93, 0x3e16c740, v106
	v_add_f32_e32 v107, v110, v107
	v_exp_f32_e32 v93, v82
	v_fmamk_f32 v82, v94, 0x3e16c740, v106
	v_add_f32_e32 v107, v111, v107
	v_exp_f32_e32 v94, v82
	v_fmamk_f32 v82, v95, 0x3e16c740, v106
	v_add_f32_e32 v107, v112, v107
	v_exp_f32_e32 v95, v82
	v_fmamk_f32 v82, v96, 0x3e16c740, v106
	v_add_f32_e32 v107, v113, v107
	v_exp_f32_e32 v96, v82
	v_fmamk_f32 v82, v97, 0x3e16c740, v106
	v_add_f32_e32 v107, v122, v107
	v_exp_f32_e32 v97, v82
	v_cvt_pk_bf16_f32 v82, v90, v91
	v_add_f32_e32 v90, v90, v107
	v_add_f32_e32 v90, v91, v90
	v_fmamk_f32 v66, v66, 0x3e16c740, v106
	v_add_f32_e32 v90, v92, v90
	v_exp_f32_e32 v91, v66
	v_fmamk_f32 v66, v67, 0x3e16c740, v106
	v_cvt_pk_bf16_f32 v83, v92, v93
	v_add_f32_e32 v90, v93, v90
	v_exp_f32_e32 v92, v66
	v_fmamk_f32 v66, v68, 0x3e16c740, v106
	v_add_f32_e32 v90, v94, v90
	v_exp_f32_e32 v93, v66
	v_fmamk_f32 v66, v69, 0x3e16c740, v106
	v_cvt_pk_bf16_f32 v84, v94, v95
	v_add_f32_e32 v90, v95, v90
	v_exp_f32_e32 v94, v66
	v_fmamk_f32 v66, v70, 0x3e16c740, v106
	v_add_f32_e32 v90, v96, v90
	v_exp_f32_e32 v95, v66
	v_fmamk_f32 v66, v71, 0x3e16c740, v106
	v_cvt_pk_bf16_f32 v85, v96, v97
	v_add_f32_e32 v90, v97, v90
	v_exp_f32_e32 v96, v66
	v_fmamk_f32 v66, v72, 0x3e16c740, v106
	v_exp_f32_e32 v97, v66
	v_fmamk_f32 v66, v73, 0x3e16c740, v106
	v_add_f32_e32 v90, v91, v90
	v_exp_f32_e32 v107, v66
	v_fmamk_f32 v66, v74, 0x3e16c740, v106
	v_add_f32_e32 v90, v92, v90
	v_exp_f32_e32 v74, v66
	v_fmamk_f32 v66, v75, 0x3e16c740, v106
	v_add_f32_e32 v90, v93, v90
	v_exp_f32_e32 v75, v66
	v_fmamk_f32 v66, v76, 0x3e16c740, v106
	v_add_f32_e32 v90, v94, v90
	v_exp_f32_e32 v76, v66
	v_fmamk_f32 v66, v77, 0x3e16c740, v106
	v_add_f32_e32 v90, v95, v90
	v_exp_f32_e32 v77, v66
	v_fmamk_f32 v66, v78, 0x3e16c740, v106
	v_add_f32_e32 v90, v96, v90
	v_exp_f32_e32 v78, v66
	v_fmamk_f32 v66, v79, 0x3e16c740, v106
	v_add_f32_e32 v90, v97, v90
	v_exp_f32_e32 v79, v66
	v_fmamk_f32 v66, v80, 0x3e16c740, v106
	v_add_f32_e32 v90, v107, v90
	v_exp_f32_e32 v80, v66
	v_cvt_pk_bf16_f32 v66, v74, v75
	v_add_f32_e32 v74, v74, v90
	v_add_f32_e32 v74, v75, v74
	v_fmac_f32_e32 v106, 0x3e16c740, v81
	v_add_f32_e32 v74, v76, v74
	v_exp_f32_e32 v81, v106
	v_add_f32_e32 v74, v77, v74
	v_add_f32_e32 v74, v78, v74
	v_add_f32_e32 v74, v79, v74
	v_add_f32_e32 v74, v80, v74
	v_cvt_pk_bf16_f32 v71, v93, v94
	v_add_f32_e32 v74, v81, v74
	v_add3_u32 v94, s7, v234, v0
	v_cvt_pk_bf16_f32 v70, v91, v92
	v_cvt_pk_bf16_f32 v67, v76, v77
	v_cvt_pk_bf16_f32 v68, v78, v79
	v_cvt_pk_bf16_f32 v69, v80, v81
	v_add_f32_e32 v236, v236, v74
	ds_read_b128 v[74:77], v94 offset:17920
	ds_read_b128 v[78:81], v94 offset:13312
	ds_read_b128 v[90:93], v94 offset:13344
	v_cvt_pk_bf16_f32 v119, v242, v243
	v_cvt_pk_bf16_f32 v120, v244, v245
	v_cvt_pk_bf16_f32 v121, v246, v247
	v_cvt_pk_bf16_f32 v87, v109, v110
	v_cvt_pk_bf16_f32 v88, v111, v112
	v_cvt_pk_bf16_f32 v89, v113, v122
	s_waitcnt lgkmcnt(2)
	v_mfma_f32_32x32x16_bf16 v[2:17], v[74:77], v[118:121], v[2:17]
	v_cvt_pk_bf16_f32 v102, v123, v124
	v_cvt_pk_bf16_f32 v103, v125, v126
	v_cvt_pk_bf16_f32 v104, v127, v128
	v_cvt_pk_bf16_f32 v105, v129, v240
	v_cvt_pk_bf16_f32 v72, v95, v96
	v_cvt_pk_bf16_f32 v73, v97, v107
	s_add_i32 s1, s1, 1
	v_mfma_f32_32x32x16_bf16 v[34:49], v[74:77], v[86:89], v[34:49]
	ds_read_b128 v[74:77], v94 offset:17952
	s_add_i32 s6, s6, 64
	v_lshl_add_u64 v[208:209], v[208:209], 0, s[76:77]
	v_lshl_add_u64 v[210:211], v[210:211], 0, s[76:77]
	v_lshl_add_u64 v[212:213], v[212:213], 0, s[84:85]
	v_lshl_add_u64 v[214:215], v[214:215], 0, s[84:85]
	v_lshl_add_u64 v[216:217], v[216:217], 0, s[84:85]
	s_waitcnt lgkmcnt(2)
	v_mfma_f32_32x32x16_bf16 v[50:65], v[78:81], v[86:89], v[50:65]
	s_cmp_lg_u32 s21, s1
	v_mfma_f32_32x32x16_bf16 v[18:33], v[78:81], v[118:121], v[18:33]
	s_waitcnt lgkmcnt(1)
	v_mfma_f32_32x32x16_bf16 v[50:65], v[90:93], v[82:85], v[50:65]
	s_waitcnt lgkmcnt(0)
	v_mfma_f32_32x32x16_bf16 v[34:49], v[74:77], v[82:85], v[34:49]
	v_mfma_f32_32x32x16_bf16 v[18:33], v[90:93], v[114:117], v[18:33]
	v_mfma_f32_32x32x16_bf16 v[2:17], v[74:77], v[114:117], v[2:17]
	ds_read_b128 v[74:77], v94 offset:13376
	ds_read_b128 v[78:81], v94 offset:17984
	s_waitcnt lgkmcnt(1)
	v_mfma_f32_32x32x16_bf16 v[50:65], v[74:77], v[70:73], v[50:65]
	s_waitcnt lgkmcnt(0)
	v_mfma_f32_32x32x16_bf16 v[34:49], v[78:81], v[70:73], v[34:49]
	v_mfma_f32_32x32x16_bf16 v[18:33], v[74:77], v[102:105], v[18:33]
	ds_read_b128 v[70:73], v94 offset:13408
	ds_read_b128 v[74:77], v94 offset:18016
	s_waitcnt lgkmcnt(0)
	s_barrier
	v_mfma_f32_32x32x16_bf16 v[2:17], v[78:81], v[102:105], v[2:17]
	v_mfma_f32_32x32x16_bf16 v[50:65], v[70:73], v[66:69], v[50:65]
	v_mfma_f32_32x32x16_bf16 v[34:49], v[74:77], v[66:69], v[34:49]
	v_mfma_f32_32x32x16_bf16 v[18:33], v[70:73], v[98:101], v[18:33]
	v_mfma_f32_32x32x16_bf16 v[2:17], v[74:77], v[98:101], v[2:17]
	s_cbranch_scc0 .LBB0_663

; #define MFMA(a, b, c) __builtin_amdgcn_mfma_f32_32x32x16_bf16((a), (b), (c), 0, 0, 0)
; template <int DQK, bool BAND, int QT> ...
;     ...
;       f32x16 s[2][QT];
; #pragma unroll
;       for (int a = 0; a < 2; ++a)
; #pragma unroll
;         for (int b = 0; b < QT; ++b)
; #pragma unroll
;           for (int r = 0; r < 16; ++r) s[a][b][r] = 0.f;
; #pragma unroll
;       for (int ks = 0; ks < NKS; ++ks) {
;         const bf16x8 k0 = *(const bf16x8*)(st + k_rd + ks * 32);
;         const bf16x8 k1 = *(const bf16x8*)(st + k_rd + 32 * KROW + ks * 32);
; #pragma unroll
;         for (int qt = 0; qt < QT; ++qt) {
;           s[0][qt] = MFMA(k0, qf[qt][ks], s[0][qt]);
;           s[1][qt] = MFMA(k1, qf[qt][ks], s[1][qt]);
;         }
;       }
;       __builtin_amdgcn_s_setprio(3);
;       bf16x8 pf[QT][4];
;       const float cc = BAND ? 1.0f : scale_log2;
;       const float th = BAND ? 8.0f : 8.0f / scale_log2;
; #pragma unroll
;       for (int qt = 0; qt < QT; ++qt) {
;         if (BAND) {
; #pragma unroll
;           for (int a = 0; a < 2; ++a)
; #pragma unroll
;             for (int r = 0; r < 16; ++r) {
;               const int kidx = kt + 32 * a + (r & 7) + 8 * h + 16 * (r >> 3);
;               const int rel = kidx - (qw0 + qt * 32 + ql);
;               const bool ok = (rel >= -64) && (rel <= 64);
;               const int bi = ok ? rel + 64 : 0;
;               s[a][qt][r] = ok ? fmaf(s[a][qt][r], scale_log2, bias_l[bi]) : -1e30f;
;             }
;         }
;         float mx = s[0][qt][0];
; #pragma unroll
;         for (int r = 1; r < 16; ++r) mx = fmaxf(mx, s[0][qt][r]);
; #pragma unroll
;         for (int r = 0; r < 16; ++r) mx = fmaxf(mx, s[1][qt][r]);
;         mx = fmaxf(mx, __shfl_xor(mx, 32));
;         if (__builtin_amdgcn_ballot_w64(mx > m[qt] + th) != 0) {
;           const float mn = fmaxf(m[qt], mx);
;           const float alpha = __builtin_amdgcn_exp2f((m[qt] - mn) * cc);
;           m[qt] = mn;
;           l[qt] *= alpha;
; #pragma unroll
;           for (int r = 0; r < 16; ++r) { o[0][qt][r] *= alpha; o[1][qt][r] *= alpha; }
;         }
.LBB0_844:
	s_bitcmp1_b32 s1, 0
	s_cselect_b32 s7, 0x5800, 0
	s_add_i32 s7, s7, 0
	v_add3_u32 v239, s7, v235, v0
	ds_read_b128 v[98:101], v239 offset:6656
	ds_read_b128 v[102:105], v239
	ds_read_b128 v[240:243], v239 offset:32
	ds_read_b128 v[244:247], v239 offset:6688
	s_waitcnt lgkmcnt(3)
	v_mfma_f32_32x32x16_bf16 v[66:81], v[98:101], v[142:145], 0
	s_waitcnt lgkmcnt(2)
	v_mfma_f32_32x32x16_bf16 v[82:97], v[102:105], v[142:145], 0
	v_mfma_f32_32x32x16_bf16 v[114:129], v[102:105], v[174:177], 0
	v_mfma_f32_32x32x16_bf16 v[98:113], v[98:101], v[174:177], 0
	s_waitcnt lgkmcnt(1)
	v_mfma_f32_32x32x16_bf16 v[82:97], v[240:243], v[150:153], v[82:97]
	s_waitcnt lgkmcnt(0)
	v_mfma_f32_32x32x16_bf16 v[66:81], v[244:247], v[150:153], v[66:81]
	v_mfma_f32_32x32x16_bf16 v[114:129], v[240:243], v[178:181], v[114:129]
	v_mfma_f32_32x32x16_bf16 v[98:113], v[244:247], v[178:181], v[98:113]
	ds_read_b128 v[240:243], v239 offset:64
	ds_read_b128 v[244:247], v239 offset:6720
	s_waitcnt lgkmcnt(1)
	v_mfma_f32_32x32x16_bf16 v[82:97], v[240:243], v[154:157], v[82:97]
	s_waitcnt lgkmcnt(0)
	v_mfma_f32_32x32x16_bf16 v[66:81], v[244:247], v[154:157], v[66:81]
	v_mfma_f32_32x32x16_bf16 v[114:129], v[240:243], v[182:185], v[114:129]
	v_mfma_f32_32x32x16_bf16 v[98:113], v[244:247], v[182:185], v[98:113]
	ds_read_b128 v[240:243], v239 offset:96
	ds_read_b128 v[244:247], v239 offset:6752
	s_waitcnt lgkmcnt(1)
	v_mfma_f32_32x32x16_bf16 v[82:97], v[240:243], v[158:161], v[82:97]
	s_waitcnt lgkmcnt(0)
	v_mfma_f32_32x32x16_bf16 v[66:81], v[244:247], v[158:161], v[66:81]
	v_mfma_f32_32x32x16_bf16 v[114:129], v[240:243], v[186:189], v[114:129]
	v_mfma_f32_32x32x16_bf16 v[98:113], v[244:247], v[186:189], v[98:113]
	ds_read_b128 v[240:243], v239 offset:128
	ds_read_b128 v[244:247], v239 offset:6784
	s_waitcnt lgkmcnt(1)
	v_mfma_f32_32x32x16_bf16 v[82:97], v[240:243], v[162:165], v[82:97]
	s_waitcnt lgkmcnt(0)
	v_mfma_f32_32x32x16_bf16 v[66:81], v[244:247], v[162:165], v[66:81]
	v_mfma_f32_32x32x16_bf16 v[114:129], v[240:243], v[190:193], v[114:129]
	v_mfma_f32_32x32x16_bf16 v[98:113], v[244:247], v[190:193], v[98:113]
	ds_read_b128 v[240:243], v239 offset:160
	ds_read_b128 v[244:247], v239 offset:6816
	s_waitcnt lgkmcnt(1)
	v_mfma_f32_32x32x16_bf16 v[82:97], v[240:243], v[166:169], v[82:97]
	s_waitcnt lgkmcnt(0)
	v_mfma_f32_32x32x16_bf16 v[66:81], v[244:247], v[166:169], v[66:81]
	v_mfma_f32_32x32x16_bf16 v[114:129], v[240:243], v[194:197], v[114:129]
	v_mfma_f32_32x32x16_bf16 v[98:113], v[244:247], v[194:197], v[98:113]
	s_setprio 3
	s_nop 6
	v_max_f32_e32 v239, v82, v83
	v_max3_f32 v239, v239, v84, v85
	v_max3_f32 v239, v239, v86, v87
	v_max3_f32 v239, v239, v88, v89
	v_max3_f32 v239, v239, v90, v91
	v_max3_f32 v239, v239, v92, v93
	v_max3_f32 v239, v239, v94, v95
	v_max3_f32 v239, v239, v96, v97
	v_max3_f32 v239, v239, v66, v67
	v_max3_f32 v239, v239, v68, v69
	v_max3_f32 v239, v239, v70, v71
	v_max3_f32 v239, v239, v72, v73
	v_max3_f32 v239, v239, v74, v75
	v_max3_f32 v239, v239, v76, v77
	v_max3_f32 v239, v239, v78, v79
	v_max3_f32 v239, v239, v80, v81
	v_add_f32_e32 v240, 0x4259535f, v237
	v_cmp_gt_f32_e32 vcc, v239, v240
	s_cbranch_vccz .LBB0_846
	ds_bpermute_b32 v240, v203, v239
	s_waitcnt lgkmcnt(0)
	v_max_f32_e32 v240, v240, v240
	v_max_f32_e32 v239, v239, v240
	v_max_f32_e32 v239, v239, v239
	v_max_f32_e32 v240, v237, v237
	v_max_f32_e32 v239, v240, v239
	v_sub_f32_e32 v237, v237, v239
	v_mul_f32_e32 v237, 0x3e16c740, v237
	v_exp_f32_e32 v240, v237
	v_mov_b32_e32 v237, v239
	v_mul_f32_e32 v236, v236, v240
	v_pk_mul_f32 v[64:65], v[64:65], v[240:241] op_sel_hi:[1,0]
	v_pk_mul_f32 v[62:63], v[62:63], v[240:241] op_sel_hi:[1,0]
	v_pk_mul_f32 v[60:61], v[60:61], v[240:241] op_sel_hi:[1,0]
	v_pk_mul_f32 v[58:59], v[58:59], v[240:241] op_sel_hi:[1,0]
	v_pk_mul_f32 v[56:57], v[56:57], v[240:241] op_sel_hi:[1,0]
	v_pk_mul_f32 v[54:55], v[54:55], v[240:241] op_sel_hi:[1,0]
	v_pk_mul_f32 v[52:53], v[52:53], v[240:241] op_sel_hi:[1,0]
	v_pk_mul_f32 v[50:51], v[50:51], v[240:241] op_sel_hi:[1,0]
	v_pk_mul_f32 v[48:49], v[48:49], v[240:241] op_sel_hi:[1,0]
	v_pk_mul_f32 v[46:47], v[46:47], v[240:241] op_sel_hi:[1,0]
	v_pk_mul_f32 v[44:45], v[44:45], v[240:241] op_sel_hi:[1,0]
	v_pk_mul_f32 v[42:43], v[42:43], v[240:241] op_sel_hi:[1,0]
	v_pk_mul_f32 v[40:41], v[40:41], v[240:241] op_sel_hi:[1,0]
	v_pk_mul_f32 v[38:39], v[38:39], v[240:241] op_sel_hi:[1,0]
	v_pk_mul_f32 v[36:37], v[36:37], v[240:241] op_sel_hi:[1,0]
	v_pk_mul_f32 v[34:35], v[34:35], v[240:241] op_sel_hi:[1,0]
.LBB0_846:
	v_max_f32_e32 v239, v114, v115
	v_max3_f32 v239, v239, v116, v117
	v_max3_f32 v239, v239, v118, v119
	v_max3_f32 v239, v239, v120, v121
	v_max3_f32 v239, v239, v122, v123
	v_max3_f32 v239, v239, v124, v125
	v_max3_f32 v239, v239, v126, v127
	v_max3_f32 v239, v239, v128, v129
	v_max3_f32 v239, v239, v98, v99
	v_max3_f32 v239, v239, v100, v101
	v_max3_f32 v239, v239, v102, v103
	v_max3_f32 v239, v239, v104, v105
	v_max3_f32 v239, v239, v106, v107
	v_max3_f32 v239, v239, v108, v109
	v_max3_f32 v239, v239, v110, v111
	v_max3_f32 v239, v239, v112, v113
	v_add_f32_e32 v240, 0x4259535f, v238
	v_cmp_gt_f32_e32 vcc, v239, v240
	s_cbranch_vccz .LBB0_848
	ds_bpermute_b32 v240, v203, v239
	s_waitcnt lgkmcnt(0)
	v_max_f32_e32 v240, v240, v240
	v_max_f32_e32 v239, v239, v240
	v_max_f32_e32 v239, v239, v239
	v_max_f32_e32 v240, v238, v238
	v_max_f32_e32 v239, v240, v239
	v_sub_f32_e32 v238, v238, v239
	v_mul_f32_e32 v238, 0x3e16c740, v238
	v_exp_f32_e32 v238, v238
	s_nop 0
	v_mul_f32_e32 v207, v207, v238
	v_pk_mul_f32 v[32:33], v[32:33], v[238:239] op_sel_hi:[1,0]
	v_pk_mul_f32 v[30:31], v[30:31], v[238:239] op_sel_hi:[1,0]
	v_pk_mul_f32 v[28:29], v[28:29], v[238:239] op_sel_hi:[1,0]
	v_pk_mul_f32 v[26:27], v[26:27], v[238:239] op_sel_hi:[1,0]
	v_pk_mul_f32 v[24:25], v[24:25], v[238:239] op_sel_hi:[1,0]
	v_pk_mul_f32 v[22:23], v[22:23], v[238:239] op_sel_hi:[1,0]
	v_pk_mul_f32 v[20:21], v[20:21], v[238:239] op_sel_hi:[1,0]
	v_pk_mul_f32 v[18:19], v[18:19], v[238:239] op_sel_hi:[1,0]
	v_pk_mul_f32 v[16:17], v[16:17], v[238:239] op_sel_hi:[1,0]
	v_pk_mul_f32 v[14:15], v[14:15], v[238:239] op_sel_hi:[1,0]
	v_pk_mul_f32 v[12:13], v[12:13], v[238:239] op_sel_hi:[1,0]
	v_pk_mul_f32 v[10:11], v[10:11], v[238:239] op_sel_hi:[1,0]
	v_pk_mul_f32 v[8:9], v[8:9], v[238:239] op_sel_hi:[1,0]
	v_pk_mul_f32 v[6:7], v[6:7], v[238:239] op_sel_hi:[1,0]
	v_pk_mul_f32 v[4:5], v[4:5], v[238:239] op_sel_hi:[1,0]
	v_pk_mul_f32 v[2:3], v[2:3], v[238:239] op_sel_hi:[1,0]
	v_mov_b32_e32 v238, v239
